# speedup vs baseline: 1.0023x; 1.0023x over previous
; __global__ void __launch_bounds__(NTHR, 2) mega(Params p) {
;     ...
;         for (int rep = 0; rep < REP_ATTN; ++rep)
;         for (int it = bid; it < 1024; it += nblk) {
;           const int rnd = it / nblk, b = it % nblk;
;           int grpi, qb;
;           if (nblk == 256) {
;             const int xcd = b & 7, sub = b >> 3;
;             const int gpr = 256 / qpb;
;             const int gx = gpr / 8;
;             grpi = rnd * gpr + xcd * gx + sub / qpb; qb = sub % qpb;
;           } else { grpi = it / qpb; qb = it % qpb; }
;           const int sj = grpi >> 3, h = grpi & 7;
;           const size_t r0 = (size_t)sj * S + qb * 256;
;           const u16* kvb = KVb + (size_t)sj * S * 2048 + h * 256;
;           __syncthreads();
.LBB0_480:
	s_or_b64 exec, exec, s[0:1]
	v_readlane_b32 s0, v253, 16
	v_readlane_b32 s1, v253, 17
	s_and_b64 vcc, exec, s[0:1]
	s_barrier
	s_cbranch_vccnz .LBB0_505
	v_readfirstlane_b32 s24, v181
	s_nop 3
	s_bfe_u32 s24, s24, 0x40006
	s_cmp_ge_u32 s24, 4
	s_cbranch_scc0 .Lattn_prio_done
	s_setprio 1
.Lattn_prio_done:
	v_readlane_b32 s0, v253, 14
	s_mov_b32 s30, s0
	v_readlane_b32 s1, v253, 15
	s_branch .LBB0_483

; template <int STAGE_, int N2> ...
;     ...
;   const int row0 = tid >> 4, c16 = tid & 15;
;   bf16x8 stg[NL];
;     ...
;   int it = bid;
;   if (it < n_items) FFT_ISSUE(it);
.LBB0_505:
	s_setprio 0
	v_readlane_b32 s6, v252, 22
	v_readlane_b32 s7, v252, 23
	s_mov_b64 s[0:1], -1
	s_and_b64 vcc, exec, s[6:7]
	s_cbranch_vccz .LBB0_514
	v_readlane_b32 s0, v253, 16
	v_mov_b32_e32 v2, v181
	v_readlane_b32 s1, v253, 17
	s_and_b64 vcc, exec, s[0:1]
	v_readfirstlane_b32 s0, v2
	s_cbranch_vccnz .LBB0_513
	v_bfe_u32 v3, v2, 5, 1
	v_bfe_u32 v0, v2, 2, 2
	v_lshl_or_b32 v0, v3, 3, v0
	v_ashrrev_i32_e32 v10, 4, v2
	v_mul_u32_u24_e32 v8, 0x140, v0
	v_ashrrev_i32_e32 v0, 31, v2
	v_add_u32_e32 v6, 32, v10
	v_lshrrev_b32_e32 v0, 25, v0
	v_ashrrev_i32_e32 v7, 31, v6
	v_add_u32_e32 v0, v10, v0
	v_lshrrev_b32_e32 v7, 25, v7
	v_ashrrev_i32_e32 v0, 7, v0
	v_add_u32_e32 v7, v6, v7
	v_mul_i32_i24_e32 v4, 0x80, v0
	v_ashrrev_i32_e32 v11, 7, v7
	v_sub_u32_e32 v122, v10, v4
	v_readlane_b32 s1, v254, 47
	v_mul_i32_i24_e32 v7, 0x80, v11
	v_sub_u32_e32 v123, v6, v7
	v_add_u32_e32 v4, s1, v122
	v_ashrrev_i32_e32 v5, 31, v4
	v_readlane_b32 s6, v254, 45
	v_add_u32_e32 v6, s1, v123
	v_lshlrev_b64 v[4:5], 11, v[4:5]
	v_readlane_b32 s7, v254, 46
	v_lshlrev_b32_e32 v66, 9, v0
	v_ashrrev_i32_e32 v7, 31, v6
	v_and_b32_e32 v9, 15, v2
	v_lshl_add_u64 v[4:5], s[6:7], 0, v[4:5]
	v_ashrrev_i32_e32 v67, 31, v66
	v_lshlrev_b64 v[6:7], 11, v[6:7]
	v_lshlrev_b32_e32 v68, 9, v11
	v_lshl_add_u64 v[4:5], v[66:67], 1, v[4:5]
	v_lshlrev_b32_e32 v0, 4, v9
	v_lshl_add_u64 v[6:7], s[6:7], 0, v[6:7]
	v_ashrrev_i32_e32 v69, 31, v68
	v_lshl_add_u64 v[4:5], v[4:5], 0, v[0:1]
	v_lshl_add_u64 v[6:7], v[68:69], 1, v[6:7]
	v_lshl_add_u64 v[6:7], v[6:7], 0, v[0:1]
	global_load_dwordx4 v[34:37], v[4:5], off
	global_load_dwordx4 v[38:41], v[6:7], off
	v_add_u32_e32 v4, 64, v10
	v_ashrrev_i32_e32 v5, 31, v4
	v_lshrrev_b32_e32 v5, 25, v5
	v_add_u32_e32 v5, v4, v5
	v_ashrrev_i32_e32 v6, 7, v5
	v_mul_i32_i24_e32 v5, 0x80, v6
	v_lshlrev_b32_e32 v70, 9, v6
	v_add_u32_e32 v6, 0x60, v10
	v_ashrrev_i32_e32 v7, 31, v6
	v_lshrrev_b32_e32 v7, 25, v7
	v_add_u32_e32 v7, v6, v7
	v_ashrrev_i32_e32 v11, 7, v7
	v_sub_u32_e32 v124, v4, v5
	v_mul_i32_i24_e32 v7, 0x80, v11
	v_add_u32_e32 v4, s1, v124
	v_sub_u32_e32 v125, v6, v7
	v_ashrrev_i32_e32 v5, 31, v4
	v_add_u32_e32 v6, s1, v125
	v_lshlrev_b64 v[4:5], 11, v[4:5]
	v_ashrrev_i32_e32 v7, 31, v6
	v_lshl_add_u64 v[4:5], s[6:7], 0, v[4:5]
	v_ashrrev_i32_e32 v71, 31, v70
	v_lshlrev_b64 v[6:7], 11, v[6:7]
	v_lshlrev_b32_e32 v72, 9, v11
	v_lshl_add_u64 v[4:5], v[70:71], 1, v[4:5]
	v_lshl_add_u64 v[6:7], s[6:7], 0, v[6:7]
	v_ashrrev_i32_e32 v73, 31, v72
	v_lshl_add_u64 v[4:5], v[4:5], 0, v[0:1]
	v_lshl_add_u64 v[6:7], v[72:73], 1, v[6:7]
	v_lshl_add_u64 v[6:7], v[6:7], 0, v[0:1]
	global_load_dwordx4 v[42:45], v[4:5], off
	global_load_dwordx4 v[46:49], v[6:7], off
	v_add_u32_e32 v4, 0x80, v10
	v_ashrrev_i32_e32 v5, 31, v4
	v_lshrrev_b32_e32 v5, 25, v5
	v_add_u32_e32 v5, v4, v5
	v_ashrrev_i32_e32 v6, 7, v5
	v_mul_i32_i24_e32 v5, 0x80, v6
	v_lshlrev_b32_e32 v74, 9, v6
	v_add_u32_e32 v6, 0xa0, v10
	v_ashrrev_i32_e32 v7, 31, v6
	v_lshrrev_b32_e32 v7, 25, v7
	v_add_u32_e32 v7, v6, v7
	v_ashrrev_i32_e32 v11, 7, v7
	v_sub_u32_e32 v126, v4, v5
	v_mul_i32_i24_e32 v7, 0x80, v11
	v_add_u32_e32 v4, s1, v126
	v_sub_u32_e32 v127, v6, v7
	v_ashrrev_i32_e32 v5, 31, v4
	v_add_u32_e32 v6, s1, v127
	v_lshlrev_b64 v[4:5], 11, v[4:5]
	v_ashrrev_i32_e32 v7, 31, v6
	v_lshl_add_u64 v[4:5], s[6:7], 0, v[4:5]
	v_ashrrev_i32_e32 v75, 31, v74
	v_lshlrev_b64 v[6:7], 11, v[6:7]
	v_lshlrev_b32_e32 v76, 9, v11
	v_lshl_add_u64 v[4:5], v[74:75], 1, v[4:5]
	v_lshl_add_u64 v[6:7], s[6:7], 0, v[6:7]
	v_ashrrev_i32_e32 v77, 31, v76
	v_lshl_add_u64 v[4:5], v[4:5], 0, v[0:1]
	v_lshl_add_u64 v[6:7], v[76:77], 1, v[6:7]
	v_lshl_add_u64 v[6:7], v[6:7], 0, v[0:1]
	global_load_dwordx4 v[50:53], v[4:5], off
	global_load_dwordx4 v[54:57], v[6:7], off
	v_add_u32_e32 v4, 0xc0, v10
	v_ashrrev_i32_e32 v5, 31, v4
	v_lshrrev_b32_e32 v5, 25, v5
	v_add_u32_e32 v5, v4, v5
	v_ashrrev_i32_e32 v6, 7, v5
	v_mul_i32_i24_e32 v5, 0x80, v6
	v_lshlrev_b32_e32 v78, 9, v6
	v_add_u32_e32 v6, 0xe0, v10
	v_ashrrev_i32_e32 v7, 31, v6
	v_lshrrev_b32_e32 v7, 25, v7
	v_add_u32_e32 v7, v6, v7
; template <int STAGE_, int N2> ...
;     ...
;   const int g = lane >> 4, i15 = lane & 15, rr = i15 >> 2, cc = i15 & 3;
;   const int tb = (int)(uintptr_t)g_lds + (8 * hi + rr) * FROW + (nbk * 32 + 16 * (g & 1) + 4 * cc) * 2;
;   const int row0 = tid >> 4, c16 = tid & 15;
;   bf16x8 stg[NL];
;     ...
;   int it = bid;
;   if (it < n_items) FFT_ISSUE(it);
;   for (; it < n_items; it += nblk) {
;     __syncthreads();
; #pragma unroll
;     for (int i = 0; i < NL; ++i) *reinterpret_cast<bf16x8*>(g_lds + (row0 + 32 * i) * FROW + c16 * 16) = stg[i];
;     __syncthreads();
;     FFT_DECODE(it, sj, sub, nb)
;     u16* dst = dstbase + (long)sj * S * ldd + nb * 128;
;     if (it + nblk < n_items) FFT_ISSUE(it + nblk);
;     f32x16 acc[MB];
; #pragma unroll
;     for (int b = 0; b < MB; ++b) acc[b] = f32x16{};
; #pragma unroll
;     for (int k4 = 0; k4 < NKS; k4 += 4) {
;       s16x4 t0[4], t1[4];
; #pragma unroll
;       for (int u = 0; u < 4; ++u) { t0[u] = tr_read_dyn(tb + (k4 + u) * 16 * FROW); t1[u] = tr_read_dyn(tb + (k4 + u) * 16 * FROW + 4 * FROW); }
;       if constexpr (!CACHE_A) {
; #pragma unroll
;         for (int b = 0; b < MB; ++b) {
;           const int mrow = (STAGE_ == 1 ? (mb0 * 32 + b * 64) : ((mb0 + 2 * b) * 32)) + r32;
; #pragma unroll
;           for (int u = 0; u < 4; ++u) av[b][u] = *reinterpret_cast<const bf16x8*>(Fm + (long)mrow * LDF + (k4 + u) * 16 + hi * 8);
	v_ashrrev_i32_e32 v11, 7, v7
	v_sub_u32_e32 v128, v4, v5
	v_mul_i32_i24_e32 v7, 0x80, v11
	v_add_u32_e32 v4, s1, v128
	v_sub_u32_e32 v129, v6, v7
	v_ashrrev_i32_e32 v5, 31, v4
	v_add_u32_e32 v6, s1, v129
	v_lshlrev_b64 v[4:5], 11, v[4:5]
	v_ashrrev_i32_e32 v7, 31, v6
	v_lshl_add_u64 v[4:5], s[6:7], 0, v[4:5]
	v_ashrrev_i32_e32 v79, 31, v78
	v_lshlrev_b64 v[6:7], 11, v[6:7]
	v_lshlrev_b32_e32 v80, 9, v11
	v_lshl_add_u64 v[4:5], v[78:79], 1, v[4:5]
	v_lshl_add_u64 v[6:7], s[6:7], 0, v[6:7]
	v_ashrrev_i32_e32 v81, 31, v80
	v_lshl_add_u64 v[4:5], v[4:5], 0, v[0:1]
	v_lshl_add_u64 v[6:7], v[80:81], 1, v[6:7]
	v_lshl_add_u64 v[6:7], v[6:7], 0, v[0:1]
	global_load_dwordx4 v[58:61], v[4:5], off
	global_load_dwordx4 v[62:65], v[6:7], off
	s_cmp_lg_u32 16, -1
	s_cselect_b32 s1, 16, 0
	s_ashr_i32 s6, s0, 2
	v_lshlrev_b32_e32 v5, 2, v2
	s_and_b32 s7, s6, 0xffffffe0
	v_and_b32_e32 v4, 16, v2
	v_and_b32_e32 v5, 12, v5
	v_or3_b32 v4, v4, v5, s7
	v_lshlrev_b32_e32 v4, 1, v4
	s_lshr_b32 s0, s0, 1
	v_add3_u32 v130, v8, s1, v4
	s_and_b32 s7, s0, 32
	v_readlane_b32 s0, v253, 46
	v_add_u32_e32 v131, 16, v0
	v_lshlrev_b32_e32 v0, 4, v3
	v_readlane_b32 s1, v253, 47
	v_lshlrev_b32_e32 v4, 3, v9
	v_add_u32_e32 v133, 0x500, v130
	v_lshl_add_u64 v[6:7], s[0:1], 0, v[0:1]
	v_mov_b32_e32 v0, s6
	s_movk_i32 s0, 0xffe0
	v_bfi_b32 v82, s0, v0, v2
	v_and_or_b32 v0, v2, 31, s7
	s_movk_i32 s0, 0x140
	v_lshlrev_b32_e32 v0, 9, v0
	v_mul_lo_u32 v132, v10, s0
	v_lshl_add_u64 v[84:85], v[6:7], 0, v[0:1]
	s_mov_b64 s[0:1], 0x8000
	v_lshl_add_u64 v[86:87], v[84:85], 0, s[0:1]
	s_mov_b64 s[0:1], 0x8020
	v_lshl_add_u64 v[88:89], v[84:85], 0, s[0:1]
	s_mov_b64 s[0:1], 0x8040
	v_lshl_add_u64 v[90:91], v[84:85], 0, s[0:1]
	s_mov_b64 s[0:1], 0x8060
	v_lshl_add_u64 v[92:93], v[84:85], 0, s[0:1]
	s_mov_b64 s[0:1], 0x8080
	v_lshl_add_u64 v[94:95], v[84:85], 0, s[0:1]
	s_mov_b64 s[0:1], 0x80a0
	v_lshl_add_u64 v[96:97], v[84:85], 0, s[0:1]
	s_mov_b64 s[0:1], 0x80c0
	v_lshl_add_u64 v[98:99], v[84:85], 0, s[0:1]
	s_mov_b64 s[0:1], 0x80e0
	v_lshl_add_u64 v[100:101], v[84:85], 0, s[0:1]
	s_mov_b64 s[0:1], 0x8100
	v_lshl_add_u64 v[102:103], v[84:85], 0, s[0:1]
	s_mov_b64 s[0:1], 0x8120
	v_lshl_add_u64 v[104:105], v[84:85], 0, s[0:1]
	s_mov_b64 s[0:1], 0x8140
	v_lshl_add_u64 v[106:107], v[84:85], 0, s[0:1]
	s_mov_b64 s[0:1], 0x8160
	v_lshl_add_u64 v[108:109], v[84:85], 0, s[0:1]
	s_mov_b64 s[0:1], 0x8180
	v_lshl_add_u64 v[110:111], v[84:85], 0, s[0:1]
	s_mov_b64 s[0:1], 0x81a0
	v_lshl_add_u64 v[112:113], v[84:85], 0, s[0:1]
	s_mov_b64 s[0:1], 0x81c0
	v_lshl_add_u64 v[114:115], v[84:85], 0, s[0:1]
	s_mov_b64 s[0:1], 0x81e0
	v_add_u32_e32 v5, 0x2800, v132
	v_lshl_add_u64 v[116:117], v[84:85], 0, s[0:1]
	v_lshlrev_b32_e32 v0, 19, v3
	v_readlane_b32 s0, v253, 14
	v_ashrrev_i32_e32 v83, 31, v82
	v_add_u32_e32 v134, 0x1400, v130
	v_add_u32_e32 v135, 0x1900, v130
	v_add_u32_e32 v136, 0x2800, v130
	v_add_u32_e32 v137, 0x2d00, v130
	v_add_u32_e32 v138, 0x3c00, v130
	v_add_u32_e32 v139, 0x4100, v130
	v_add_u32_e32 v140, 0x5000, v130
	v_add_u32_e32 v141, 0x5500, v130
	v_add_u32_e32 v142, 0x6400, v130
	v_add_u32_e32 v143, 0x6900, v130
	s_waitcnt vmcnt(62)
	v_add_u32_e32 v144, 0x7800, v130
	v_add_u32_e32 v145, 0x7d00, v130
	v_add_u32_e32 v146, 0x8c00, v130
	v_add_u32_e32 v147, 0x9100, v130
	v_add_u32_e32 v148, 0xa000, v130
	v_add_u32_e32 v149, 0xa500, v130
	v_add_u32_e32 v150, 0xb400, v130
	v_add_u32_e32 v151, 0xb900, v130
	v_add_u32_e32 v152, 0xc800, v130
	v_add_u32_e32 v153, 0xcd00, v130
	v_add_u32_e32 v154, 0xdc00, v130
	v_add_u32_e32 v155, 0xe100, v130
	v_add_u32_e32 v156, 0xf000, v130
	v_add_u32_e32 v157, 0xf500, v130
	v_add_u32_e32 v158, 0x10400, v130
	v_add_u32_e32 v159, 0x10900, v130
	v_add_u32_e32 v160, 0x11800, v130
	v_add_u32_e32 v161, 0x11d00, v130
	v_add_u32_e32 v162, 0x12c00, v130
	v_add_u32_e32 v163, 0x13100, v130
	v_lshl_or_b32 v164, s7, 17, v0
	v_add_u32_e32 v165, v131, v5
	v_lshlrev_b32_e32 v118, 1, v4
	v_readlane_b32 s10, v252, 5
	v_readlane_b32 s8, v254, 35
	v_readlane_b32 s11, v253, 13
	s_mov_b32 s9, s0
	v_readlane_b32 s1, v253, 15
	s_branch .LBB0_509
